# SwiGLU epilogue caches per-row rstd across tiles with same row tile; attention softmax/PV interleave; scan consumer hand-scheduled
# speedup vs baseline: 1.0257x; 1.0117x over previous
; #define PG8_BAR __builtin_amdgcn_s_barrier()
;     __host__ __device__ bool next(int i, Unit& u) const {
;         const long L = (long)i * G + c; if (L >= nwg) return false;
;         int wgid = (int)L; { const int q = nwg / NXCD, r = nwg % NXCD, xcd = wgid % NXCD, off = wgid / NXCD; wgid = (xcd < r ? xcd * (q + 1) : r * (q + 1) + (xcd - r) * q) + off; }
;         const int nig = WGM * nN, gid = wgid / nig, fm = gid * WGM, gsz = (nM - fm) < WGM ? (nM - fm) : WGM;
;         u.pm = fm + ((wgid % nig) % gsz); u.pn = (wgid % nig) / gsz; return true;
; template <class Epi, class Sched, bool ALIGN_EPI = false, bool SP2 = false>
; __device__ __forceinline__ void gemm_phase(PG8_LAS unsigned char* lds, const Gemm g, const Sched& S, const Epi& E) {
;     ...
;     const int tid = threadIdx.x + oz_, wid = __builtin_amdgcn_readfirstlane(tid >> 6), lane = tid & 63, wr = wid >> 2, wc = wid & 3, fr = lane & 15, fq = lane >> 4;
;     const int K = g.K, nt = K / BK;
;     unsigned voffA[2], voffB[2];
; #pragma unroll
;     for (int i = 0; i < 2; ++i) { int R, C; stage_rc(tid * 16 + i * 8192, R, C); const int Rb = Epi::PERM ? ((R & ~31) + perm32(R & 31)) : R;
;         voffA[i] = (unsigned)(R * K + C) * 2u; voffB[i] = (unsigned)(Rb * K + C) * 2u; }
;     const size_t kstep = (size_t)(BK * 2);
;     const size_t hstep = (size_t)HALF * K * 2;
;     const size_t tstep = 2 * hstep;
;     const unsigned ldsw = (unsigned)wid * 1024u;
;     const int aoff = lds_byte(wr * 64 + fr, fq * 8), boff = lds_byte(wc * 32 + fr, fq * 8);
;     ...
;     Unit cur, nxt; int ui = 0;
;     if (!S.next(0, cur)) return;
;     f32x4 acc[2][2][4][2];
; #pragma unroll
;     for (int a = 0; a < 2; ++a)
; #pragma unroll
;         for (int b = 0; b < 2; ++b)
; #pragma unroll
;             for (int m = 0; m < 4; ++m)
; #pragma unroll
;                 for (int n = 0; n < 2; ++n) acc[a][b][m][n] = (f32x4){0.f, 0.f, 0.f, 0.f};
;     bf16x8 At[4][2], B0[2][2], B1[2][2];
;     const char* cA = (const char*)g.A + (size_t)cur.pm * tstep; const char* cB = (const char*)g.Bt + (size_t)cur.pn * tstep;
;     S.a_ready(cur);
;     if constexpr (SP2) {
;         PG8_STAGE(PG8_SB(0, 0), cB, voffB); PG8_STAGE(PG8_SB(0, 1), cB + hstep, voffB); PG8_STAGE(PG8_SA(0, 0), cA, voffA); PG8_STAGE(PG8_SA(0, 1), cA + hstep, voffA);
;         if (wr == 1) PG8_BAR;
.LBB0_626:
	v_readlane_b32 s30, v254, 42
	s_andn2_b64 vcc, exec, s[8:9]
	v_readlane_b32 s31, v254, 43
	s_cbranch_vccnz .LBB0_652
	s_mov_b32 s98, -1
	s_movk_i32 s2, 0x1600
	s_movk_i32 s6, 0x400
	s_ashr_i32 s4, s2, 31
	s_lshr_b32 s4, s4, 24
	s_add_i32 s2, s2, s4
	s_ashr_i32 s16, s2, 8
	s_lshl_b32 s4, s16, 7
	s_mov_b32 s2, 0
	s_cmp_ge_i32 s38, s4
	s_waitcnt vmcnt(0)
	v_add_u32_e32 v14, s2, v242
	s_nop 0
	v_readfirstlane_b32 s5, v14
	s_cbranch_scc1 .LBB0_652
	v_lshlrev_b32_e32 v0, 4, v14
	v_add_u32_e32 v2, 0x2000, v0
	v_ashrrev_i32_e32 v3, 31, v2
	v_lshrrev_b32_e32 v3, 22, v3
	v_add_u32_e32 v3, v2, v3
	v_ashrrev_i32_e32 v3, 10, v3
	v_mul_i32_i24_e32 v4, 0x400, v3
	v_sub_u32_e32 v2, v2, v4
	v_lshrrev_b32_e32 v4, 4, v2
	v_bitop3_b32 v2, v4, v2, 32 bitop3:0x6c
	v_ashrrev_i32_e32 v4, 31, v2
	v_lshrrev_b32_e32 v4, 26, v4
	v_add_u32_e32 v4, v2, v4
	v_lshlrev_b32_e32 v6, 3, v3
	v_ashrrev_i32_e32 v5, 6, v4
	v_and_b32_e32 v6, -16, v6
	v_lshlrev_b32_e32 v3, 5, v3
	v_add_u32_e32 v6, v5, v6
	v_and_b32_e32 v15, 32, v3
	v_and_b32_e32 v3, 0xc0, v4
	v_and_b32_e32 v5, 3, v5
	s_mov_b32 s17, 0x7fffffe0
	v_lshrrev_b32_e32 v7, 2, v6
	v_lshlrev_b32_e32 v8, 1, v6
	v_sub_u32_e32 v2, v2, v3
	v_and_or_b32 v5, v6, s17, v5
	v_and_b32_e32 v7, 4, v7
	v_and_b32_e32 v8, 24, v8
	v_ashrrev_i16_sdwa v2, v240, sext(v2) dst_sel:DWORD dst_unused:UNUSED_PAD src0_sel:DWORD src1_sel:BYTE_0
	v_or3_b32 v5, v5, v7, v8
	v_bfe_i32 v16, v2, 0, 16
	v_mul_lo_u32 v5, v5, s6
	v_add_u32_e32 v2, v15, v16
	v_mul_lo_u32 v17, v6, s6
	v_add_lshl_u32 v154, v5, v2, 1
	v_add_lshl_u32 v156, v2, v17, 1
	v_bfe_i32 v2, v14, 27, 1
	v_lshrrev_b32_e32 v2, 22, v2
	v_add_u32_e32 v2, v0, v2
	v_and_b32_e32 v2, 0xfffffc00, v2
	v_sub_u32_e32 v0, v0, v2
	v_lshrrev_b32_e32 v2, 4, v0
	v_ashrrev_i32_e32 v4, 31, v14
	v_readlane_b32 s8, v254, 48
	v_bitop3_b32 v0, v2, v0, 32 bitop3:0x6c
	v_lshrrev_b32_e32 v4, 26, v4
	s_mul_i32 s2, s8, 0xb00000
	v_ashrrev_i32_e32 v2, 31, v0
	v_add_u32_e32 v4, v14, v4
	s_add_u32 s2, s90, s2
	v_lshrrev_b32_e32 v2, 26, v2
	v_ashrrev_i32_e32 v4, 6, v4
	v_readlane_b32 s9, v254, 49
	s_addc_u32 s22, s91, 0
	s_ashr_i32 s8, s5, 6
	s_ashr_i32 s7, s6, 31
	v_add_u32_e32 v2, v0, v2
	v_lshlrev_b32_e32 v5, 3, v4
	s_lshl_b32 s30, s16, 4
	v_readlane_b32 s20, v252, 41
	s_ashr_i32 s9, s5, 8
	s_lshl_b64 s[10:11], s[6:7], 8
	s_lshl_b64 s[12:13], s[6:7], 9
	s_lshl_b32 s23, s8, 10
	v_ashrrev_i32_e32 v3, 6, v2
	v_and_b32_e32 v5, -16, v5
	s_or_b32 s31, s30, 1
	v_readlane_b32 s21, v252, 42
	v_add_u32_e32 v5, v3, v5
	v_and_b32_e32 v3, 3, v3
	s_and_b64 s[20:21], s[20:21], exec
	v_and_or_b32 v3, v5, s17, v3
	s_cselect_b32 s17, s31, s30
	s_lshl_b32 s33, s16, 3
	v_and_b32_e32 v2, 0xc0, v2
	s_abs_i32 s39, s33
	v_sub_u32_e32 v0, v0, v2
	v_cvt_f32_u32_e32 v2, s39
	v_ashrrev_i16_sdwa v0, v240, sext(v0) dst_sel:DWORD dst_unused:UNUSED_PAD src0_sel:DWORD src1_sel:BYTE_0
	v_bfe_i32 v19, v0, 0, 16
	v_readlane_b32 s20, v252, 40
	v_rcp_iflag_f32_e32 v0, v2
	s_mul_i32 s17, s17, s20
	v_readlane_b32 s20, v252, 34
	s_sub_i32 s21, 0, s39
	v_mul_f32_e32 v0, 0x4f7ffffe, v0
	v_cvt_u32_f32_e32 v0, v0
	s_add_i32 s17, s17, s20
	s_ashr_i32 s20, s17, 31
	s_bfe_i32 s41, s16, 0x1001c
	v_readfirstlane_b32 s54, v0
	s_mul_i32 s21, s21, s54
	s_mul_hi_u32 s21, s54, s21
	s_xor_b32 s16, s20, s41
	s_abs_i32 s20, s17
	s_add_i32 s54, s54, s21
	s_mul_hi_u32 s21, s20, s54
	s_mul_i32 s42, s21, s39
	s_sub_i32 s20, s20, s42
	s_add_i32 s42, s21, 1
	s_sub_i32 s43, s20, s39
	s_cmp_ge_u32 s20, s39
	s_cselect_b32 s21, s42, s21
	s_cselect_b32 s20, s43, s20
	s_add_i32 s42, s21, 1
	s_cmp_ge_u32 s20, s39
	s_cselect_b32 s20, s42, s21
	s_xor_b32 s20, s20, s16
	s_sub_i32 s16, s20, s16
	s_lshl_b32 s20, s16, 3
	s_sub_i32 s21, 0x80, s20
	s_min_i32 s21, s21, 8
	s_abs_i32 s42, s21
	v_cvt_f32_u32_e32 v2, s42
	s_sub_i32 s44, 0, s42
	s_mul_i32 s16, s16, s33
	s_sub_i32 s16, s17, s16
	v_rcp_iflag_f32_e32 v2, v2
	s_abs_i32 s43, s16
	s_xor_b32 s17, s16, s21
	s_ashr_i32 s17, s17, 31
	v_mul_f32_e32 v2, 0x4f7ffffe, v2
	v_cvt_u32_f32_e32 v2, v2
	v_lshrrev_b32_e32 v6, 2, v5
	v_lshlrev_b32_e32 v7, 1, v5
	v_and_b32_e32 v6, 4, v6
	v_readfirstlane_b32 s45, v2
	s_mul_i32 s44, s44, s45
	s_mul_hi_u32 s44, s45, s44
	s_add_i32 s45, s45, s44
	s_mul_hi_u32 s44, s43, s45
	s_mul_i32 s45, s44, s42
	s_sub_i32 s43, s43, s45
	s_add_i32 s45, s44, 1
	s_sub_i32 s46, s43, s42
	s_cmp_ge_u32 s43, s42
	s_cselect_b32 s44, s45, s44
	s_cselect_b32 s43, s46, s43
	s_add_i32 s45, s44, 1
	s_cmp_ge_u32 s43, s42
	s_cselect_b32 s42, s45, s44
	s_xor_b32 s42, s42, s17
	s_sub_i32 s66, s42, s17
	s_mul_i32 s17, s66, s21
	s_sub_i32 s16, s16, s17
	s_add_i32 s67, s16, s20
	s_ashr_i32 s16, s67, 31
	s_mul_i32 s16, s12, s16
	s_mul_hi_u32 s17, s12, s67
	s_add_i32 s20, s17, s16
	s_lshr_b64 s[16:17], s[6:7], 23
	s_mul_i32 s17, s16, s67
	s_add_i32 s42, s20, s17
	s_ashr_i32 s17, s66, 31
	s_mul_i32 s17, s12, s17
	s_mul_hi_u32 s20, s12, s66
	s_add_i32 s17, s20, s17
	s_mul_i32 s16, s16, s66
	v_and_b32_e32 v7, 24, v7
	v_lshlrev_b32_e32 v4, 5, v4
	s_add_i32 s17, s17, s16
	s_mul_i32 s16, s12, s66
	v_or3_b32 v3, v3, v6, v7
	v_and_b32_e32 v18, 32, v4
	s_add_u32 s20, s2, s16
	v_mul_lo_u32 v3, v3, s6
	v_add_u32_e32 v4, v18, v19
	s_addc_u32 s21, s22, s17
	s_add_i32 s55, s23, 0
	v_add_lshl_u32 v0, v3, v4, 1
	s_add_i32 m0, s55, 0x10000
	s_mul_i32 s43, s12, s67
	global_load_lds_dwordx4 v0, s[20:21]
	s_add_i32 m0, s55, 0x12000
	s_add_u32 s16, s20, s10
	global_load_lds_dwordx4 v154, s[20:21]
	s_addc_u32 s17, s21, s11
	s_add_i32 m0, s55, 0x14000
	v_mul_lo_u32 v20, v5, s6
	global_load_lds_dwordx4 v0, s[16:17]
	s_add_i32 m0, s55, 0x16000
	s_add_u32 s52, s14, s43
	s_addc_u32 s53, s15, s42
	s_add_i32 s56, s55, 0x2000
	v_add_lshl_u32 v158, v4, v20, 1
	global_load_lds_dwordx4 v154, s[16:17]
	s_mov_b32 m0, s55
	s_add_u32 s42, s52, s10
	global_load_lds_dwordx4 v158, s[52:53]
	s_mov_b32 m0, s56
	s_addc_u32 s43, s53, s11
	s_add_i32 s57, s55, 0x4000
	global_load_lds_dwordx4 v156, s[52:53]
	s_mov_b32 m0, s57
	s_add_i32 s58, s55, 0x6000
	global_load_lds_dwordx4 v158, s[42:43]
	s_mov_b32 m0, s58
	v_mov_b32_e32 v155, v1
	global_load_lds_dwordx4 v156, s[42:43]
	v_mov_b32_e32 v159, v1
	v_mov_b32_e32 v157, v1
	s_cmp_eq_u32 s9, 1
	v_lshl_add_u64 v[10:11], s[20:21], 0, v[0:1]
	v_lshl_add_u64 v[6:7], s[20:21], 0, v[154:155]
	v_lshl_add_u64 v[4:5], s[16:17], 0, v[0:1]
	v_lshl_add_u64 v[2:3], s[16:17], 0, v[154:155]
	v_lshl_add_u64 v[8:9], s[52:53], 0, v[158:159]
	s_cselect_b64 s[16:17], -1, 0
	s_cmp_lg_u32 s9, 1
	v_lshl_add_u64 v[12:13], s[52:53], 0, v[156:157]
	s_cbranch_scc1 .LBB0_630
	s_barrier

; __device__ __forceinline__ void row_rstd8(const float* rsq, int row0, int fq, float (&rs)[8]) {
;     ...
;     f32x4 p[8];
; #pragma unroll
;     for (int i = 0; i < 8; ++i) p[i] = *(const f32x4*)(rsq + (size_t)(row0 + (i >> 2) * 128 + (i & 3) * 16) * 16 + 4 * fq);
;     asm volatile("" ::: "memory");
; #pragma unroll
;     for (int i = 0; i < 8; ++i) rs[i] = rsqrtf(fq_sum((p[i].x + p[i].y) + (p[i].z + p[i].w)) * (1.f / DM) + 1e-6f);
; }
;     __device__ __forceinline__ void operator()(const pg8::f32x4 (&acc)[2][2][4][2], const pg8::Unit& u, int wr, int wc, int fr, int fq) const {
;         int oz; asm volatile("v_mov_b32 %0, 0" : "=v"(oz));
;         const int row0 = u.pm * 256 + wr * 64 + fr + oz, col0 = u.pn * 128 + wc * 32 + 8 * fq;
;         float rs8[8]; row_rstd8(rsq, row0, fq, rs8);
.LBB0_644:
	s_lshl_b32 s8, s67, 8
	v_mov_b32 v130, 0
	s_and_b64 vcc, exec, s[42:43]
	v_add3_u32 v174, s8, v180, v130
	v_ashrrev_i32_e32 v175, 31, v174
	s_mov_b64 s[8:9], -1
	v_add_u32_e32 v172, 16, v174
	v_add_u32_e32 v170, 32, v174
	v_add_u32_e32 v168, 48, v174
	v_add_u32_e32 v176, 0x80, v174
	s_cbranch_vccz .LBB0_646
	s_cmp_eq_u32 s67, s98
	s_cbranch_scc1 .Lrs_hit
	v_lshlrev_b64 v[130:131], 6, v[174:175]
	v_lshl_add_u64 v[130:131], v[160:161], 0, v[130:131]
	global_load_dwordx4 v[184:187], v[130:131], off
	v_ashrrev_i32_e32 v173, 31, v172
	v_lshlrev_b64 v[132:133], 6, v[172:173]
	v_lshl_add_u64 v[132:133], v[160:161], 0, v[132:133]
	global_load_dwordx4 v[188:191], v[132:133], off
	v_ashrrev_i32_e32 v171, 31, v170
	v_lshlrev_b64 v[132:133], 6, v[170:171]
	v_lshl_add_u64 v[132:133], v[160:161], 0, v[132:133]
	v_ashrrev_i32_e32 v169, 31, v168
	global_load_dwordx4 v[150:153], v[132:133], off
	v_lshlrev_b64 v[132:133], 6, v[168:169]
	v_lshl_add_u64 v[132:133], v[160:161], 0, v[132:133]
	global_load_dwordx4 v[146:149], v[132:133], off
	v_add_u32_e32 v166, 0x80, v174
	v_ashrrev_i32_e32 v167, 31, v166
	v_lshlrev_b64 v[132:133], 6, v[166:167]
	v_lshl_add_u64 v[132:133], v[160:161], 0, v[132:133]
	global_load_dwordx4 v[142:145], v[132:133], off
	s_movk_i32 s8, 0x2000
	v_add_co_u32_e32 v130, vcc, s8, v130
	s_mov_b32 s8, 0x358637bd
	s_nop 0
	v_addc_co_u32_e32 v131, vcc, 0, v131, vcc
	global_load_dwordx4 v[138:141], v[130:131], off offset:1024
	global_load_dwordx4 v[134:137], v[130:131], off offset:2048
	s_nop 0
	global_load_dwordx4 v[130:133], v[130:131], off offset:3072
	s_mov_b32 s52, 0x3a800000
	s_mov_b32 s20, 0x45800000
	s_waitcnt vmcnt(0)
	v_mov_b32_e32 v178, v185
	v_mov_b32_e32 v179, v186
	v_mov_b32_e32 v185, v187
	v_pk_add_f32 v[178:179], v[178:179], v[184:185]
	v_mov_b32_e32 v186, v189
	v_add_f32_e32 v175, v178, v179
	ds_swizzle_b32 v177, v175 offset:swizzle(SWAP,16)
	v_mov_b32_e32 v187, v190
	v_mov_b32_e32 v189, v191
	v_pk_add_f32 v[186:187], v[186:187], v[188:189]
	s_waitcnt lgkmcnt(0)
	v_add_f32_e32 v178, v175, v177
	v_add_f32_e32 v175, v186, v187
	ds_swizzle_b32 v177, v175 offset:swizzle(SWAP,16)
	v_mov_b32_e32 v184, v178
	s_nop 1
	v_permlane32_swap_b32_e32 v178, v184
	s_waitcnt lgkmcnt(0)
	v_add_f32_e32 v179, v175, v177
	v_mov_b32_e32 v185, v179
	s_nop 1
	v_permlane32_swap_b32_e32 v179, v185
	v_pk_add_f32 v[184:185], v[178:179], v[184:185]
	v_mov_b64_e32 v[178:179], s[8:9]
	v_pk_fma_f32 v[184:185], v[184:185], s[52:53], v[178:179] op_sel_hi:[1,0,0]
	s_nop 0
	v_mul_f32_e32 v175, 0x4b800000, v184
	v_cmp_gt_f32_e64 s[8:9], s37, v184
	v_cmp_gt_f32_e32 vcc, s37, v185
	s_nop 0
	v_cndmask_b32_e64 v175, v184, v175, s[8:9]
	v_rsq_f32_e32 v184, v175
	v_mul_f32_e32 v175, 0x4b800000, v185
	v_cndmask_b32_e32 v175, v185, v175, vcc
	v_rsq_f32_e32 v185, v175
	s_nop 0
	v_pk_mul_f32 v[186:187], v[184:185], s[20:21] op_sel_hi:[1,0]
	s_nop 0
	v_cndmask_b32_e64 v184, v184, v186, s[8:9]
	v_cndmask_b32_e32 v177, v185, v187, vcc
	v_mov_b32_e32 v186, v151
	v_mov_b32_e32 v187, v152
	v_mov_b32_e32 v151, v153
	v_pk_add_f32 v[150:151], v[186:187], v[150:151]
	v_mov_b32_e32 v186, v147
	v_mov_b32_e32 v187, v148
	v_mov_b32_e32 v147, v149
	v_pk_add_f32 v[146:147], v[186:187], v[146:147]
	v_add_f32_e32 v150, v150, v151
	v_add_f32_e32 v146, v146, v147
	ds_swizzle_b32 v151, v150 offset:swizzle(SWAP,16)
	ds_swizzle_b32 v147, v146 offset:swizzle(SWAP,16)
	s_waitcnt lgkmcnt(1)
	v_add_f32_e32 v150, v150, v151
	s_waitcnt lgkmcnt(0)
; __device__ __forceinline__ void row_rstd8(const float* rsq, int row0, int fq, float (&rs)[8]) {
;     ...
;     for (int i = 0; i < 8; ++i) p[i] = *(const f32x4*)(rsq + (size_t)(row0 + (i >> 2) * 128 + (i & 3) * 16) * 16 + 4 * fq);
;     asm volatile("" ::: "memory");
; #pragma unroll
;     for (int i = 0; i < 8; ++i) rs[i] = rsqrtf(fq_sum((p[i].x + p[i].y) + (p[i].z + p[i].w)) * (1.f / DM) + 1e-6f);
	v_add_f32_e32 v151, v146, v147
	v_mov_b32_e32 v152, v150
	v_mov_b32_e32 v153, v151
	s_nop 0
	v_permlane32_swap_b32_e32 v150, v152
	v_permlane32_swap_b32_e32 v151, v153
	v_pk_add_f32 v[146:147], v[150:151], v[152:153]
	s_nop 0
	v_pk_fma_f32 v[146:147], v[146:147], s[52:53], v[178:179] op_sel_hi:[1,0,0]
	s_nop 0
	v_mul_f32_e32 v148, 0x4b800000, v146
	v_cmp_gt_f32_e64 s[8:9], s37, v146
	v_cmp_gt_f32_e32 vcc, s37, v147
	s_nop 0
	v_cndmask_b32_e64 v146, v146, v148, s[8:9]
	v_rsq_f32_e32 v148, v146
	v_mul_f32_e32 v146, 0x4b800000, v147
	v_cndmask_b32_e32 v146, v147, v146, vcc
	v_rsq_f32_e32 v149, v146
	s_nop 0
	v_pk_mul_f32 v[150:151], v[148:149], s[20:21] op_sel_hi:[1,0]
	s_nop 0
	v_cndmask_b32_e64 v147, v148, v150, s[8:9]
	v_cndmask_b32_e32 v146, v149, v151, vcc
	v_mov_b32_e32 v148, v143
	v_mov_b32_e32 v149, v144
	v_mov_b32_e32 v143, v145
	v_pk_add_f32 v[142:143], v[148:149], v[142:143]
	v_mov_b32_e32 v148, v139
	v_mov_b32_e32 v149, v140
	v_mov_b32_e32 v139, v141
	v_pk_add_f32 v[138:139], v[148:149], v[138:139]
	v_add_f32_e32 v142, v142, v143
	v_add_f32_e32 v138, v138, v139
	ds_swizzle_b32 v143, v142 offset:swizzle(SWAP,16)
	ds_swizzle_b32 v139, v138 offset:swizzle(SWAP,16)
	s_waitcnt lgkmcnt(1)
	v_add_f32_e32 v142, v142, v143
	s_waitcnt lgkmcnt(0)
	v_add_f32_e32 v143, v138, v139
	v_mov_b32_e32 v144, v142
	v_mov_b32_e32 v145, v143
	s_nop 0
	v_permlane32_swap_b32_e32 v142, v144
	v_permlane32_swap_b32_e32 v143, v145
	v_pk_add_f32 v[138:139], v[142:143], v[144:145]
	s_nop 0
	v_pk_fma_f32 v[138:139], v[138:139], s[52:53], v[178:179] op_sel_hi:[1,0,0]
	s_nop 0
	v_mul_f32_e32 v140, 0x4b800000, v138
	v_cmp_gt_f32_e64 s[8:9], s37, v138
	v_cmp_gt_f32_e32 vcc, s37, v139
	s_nop 0
	v_cndmask_b32_e64 v138, v138, v140, s[8:9]
	v_rsq_f32_e32 v140, v138
	v_mul_f32_e32 v138, 0x4b800000, v139
	v_cndmask_b32_e32 v138, v139, v138, vcc
	v_rsq_f32_e32 v141, v138
	s_nop 0
	v_pk_mul_f32 v[142:143], v[140:141], s[20:21] op_sel_hi:[1,0]
	s_nop 0
	v_cndmask_b32_e64 v139, v140, v142, s[8:9]
	v_cndmask_b32_e32 v138, v141, v143, vcc
	v_mov_b32_e32 v140, v135
	v_mov_b32_e32 v141, v136
	v_mov_b32_e32 v135, v137
	v_pk_add_f32 v[134:135], v[140:141], v[134:135]
	v_mov_b32_e32 v140, v131
	v_mov_b32_e32 v141, v132
	v_mov_b32_e32 v131, v133
	v_pk_add_f32 v[130:131], v[140:141], v[130:131]
	v_add_f32_e32 v134, v134, v135
	v_add_f32_e32 v130, v130, v131
	ds_swizzle_b32 v135, v134 offset:swizzle(SWAP,16)
	ds_swizzle_b32 v131, v130 offset:swizzle(SWAP,16)
	s_waitcnt lgkmcnt(1)
	v_add_f32_e32 v135, v134, v135
	s_waitcnt lgkmcnt(0)
	v_add_f32_e32 v134, v130, v131
	v_mov_b32_e32 v137, v135
	v_mov_b32_e32 v136, v134
	s_nop 0
	v_permlane32_swap_b32_e32 v135, v137
	v_permlane32_swap_b32_e32 v134, v136
	v_pk_add_f32 v[130:131], v[134:135], v[136:137]
	s_nop 0
	v_pk_fma_f32 v[130:131], v[130:131], s[52:53], v[178:179] op_sel_hi:[1,0,0]
	s_nop 0
	v_mul_f32_e32 v132, 0x4b800000, v131
	v_cmp_gt_f32_e64 s[8:9], s37, v131
	v_cmp_gt_f32_e32 vcc, s37, v130
	s_nop 0
	v_cndmask_b32_e64 v131, v131, v132, s[8:9]
	v_rsq_f32_e32 v131, v131
	s_nop 0
	v_mul_f32_e32 v132, 0x45800000, v131
	v_cndmask_b32_e64 v135, v131, v132, s[8:9]
	v_mul_f32_e32 v131, 0x4b800000, v130
	v_cndmask_b32_e32 v130, v130, v131, vcc
	v_rsq_f32_e32 v130, v130
	s_mov_b64 s[8:9], 0
	v_mov_b64_e32 v[132:133], v[166:167]
	v_mul_f32_e32 v131, 0x45800000, v130
	v_cndmask_b32_e32 v134, v130, v131, vcc
	v_mov_b32_e32 v226, v134
	v_mov_b32_e32 v227, v184
	v_mov_b32_e32 v228, v177
	v_mov_b32_e32 v229, v147
	v_mov_b32_e32 v230, v146
	v_mov_b32_e32 v231, v139
	v_mov_b32_e32 v232, v138
	v_mov_b32_e32 v233, v135
	s_mov_b32 s98, s67
	s_branch .LBB0_646
.Lrs_hit:
	v_add_u32_e32 v166, 0x80, v174
	v_ashrrev_i32_e32 v167, 31, v166
	v_ashrrev_i32_e32 v173, 31, v172
	v_ashrrev_i32_e32 v171, 31, v170
	v_ashrrev_i32_e32 v169, 31, v168
	v_mov_b64_e32 v[132:133], v[166:167]
	v_mov_b32_e32 v134, v226
	v_mov_b32_e32 v184, v227
	v_mov_b32_e32 v177, v228
	v_mov_b32_e32 v147, v229
	v_mov_b32_e32 v146, v230
	v_mov_b32_e32 v139, v231
	v_mov_b32_e32 v138, v232
	v_mov_b32_e32 v135, v233
	s_mov_b64 s[8:9], 0

; __global__ void __launch_bounds__(NTHR, 2) mega_fwd(Args a) {
	.amdhsa_kernel _Z8mega_fwd4Args
		.amdhsa_group_segment_fixed_size 0
		.amdhsa_private_segment_fixed_size 0
		.amdhsa_kernarg_size 544
		.amdhsa_user_sgpr_count 2
		.amdhsa_user_sgpr_dispatch_ptr 0
		.amdhsa_user_sgpr_queue_ptr 0
		.amdhsa_user_sgpr_kernarg_segment_ptr 1
		.amdhsa_user_sgpr_dispatch_id 0
		.amdhsa_user_sgpr_kernarg_preload_length 0
		.amdhsa_user_sgpr_kernarg_preload_offset 0
		.amdhsa_user_sgpr_private_segment_size 0
		.amdhsa_uses_dynamic_stack 0
		.amdhsa_enable_private_segment 0
		.amdhsa_system_sgpr_workgroup_id_x 1
		.amdhsa_system_sgpr_workgroup_id_y 0
		.amdhsa_system_sgpr_workgroup_id_z 0
		.amdhsa_system_sgpr_workgroup_info 0
		.amdhsa_system_vgpr_workitem_id 2
		.amdhsa_next_free_vgpr 256
		.amdhsa_next_free_sgpr 100
		.amdhsa_accum_offset 256
		.amdhsa_reserve_vcc 1
		.amdhsa_float_round_mode_32 0
		.amdhsa_float_round_mode_16_64 0
		.amdhsa_float_denorm_mode_32 3
		.amdhsa_float_denorm_mode_16_64 3
		.amdhsa_dx10_clamp 1
		.amdhsa_ieee_mode 1
		.amdhsa_fp16_overflow 0
		.amdhsa_tg_split 0
		.amdhsa_exception_fp_ieee_invalid_op 0
		.amdhsa_exception_fp_denorm_src 0
		.amdhsa_exception_fp_ieee_div_zero 0
		.amdhsa_exception_fp_ieee_overflow 0
		.amdhsa_exception_fp_ieee_underflow 0
		.amdhsa_exception_fp_ieee_inexact 0
		.amdhsa_exception_int_div_zero 0
	.end_amdhsa_kernel

; __global__ void __launch_bounds__(NTHR, 2) mega_fwd(Args a) {
amdhsa.kernels:
  - .agpr_count:     0
    .args:
      - .offset:         0
        .size:           288
        .value_kind:     by_value
      - .offset:         288
        .size:           4
        .value_kind:     hidden_block_count_x
      - .offset:         292
        .size:           4
        .value_kind:     hidden_block_count_y
      - .offset:         296
        .size:           4
        .value_kind:     hidden_block_count_z
      - .offset:         300
        .size:           2
        .value_kind:     hidden_group_size_x
      - .offset:         302
        .size:           2
        .value_kind:     hidden_group_size_y
      - .offset:         304
        .size:           2
        .value_kind:     hidden_group_size_z
      - .offset:         306
        .size:           2
        .value_kind:     hidden_remainder_x
      - .offset:         308
        .size:           2
        .value_kind:     hidden_remainder_y
      - .offset:         310
        .size:           2
        .value_kind:     hidden_remainder_z
      - .offset:         328
        .size:           8
        .value_kind:     hidden_global_offset_x
      - .offset:         336
        .size:           8
        .value_kind:     hidden_global_offset_y
      - .offset:         344
        .size:           8
        .value_kind:     hidden_global_offset_z
      - .offset:         352
        .size:           2
        .value_kind:     hidden_grid_dims
      - .offset:         376
        .size:           8
        .value_kind:     hidden_multigrid_sync_arg
      - .offset:         408
        .size:           4
        .value_kind:     hidden_dynamic_lds_size
    .group_segment_fixed_size: 0
    .kernarg_segment_align: 8
    .kernarg_segment_size: 544
    .language:       OpenCL C
    .language_version:
      - 2
      - 0
    .max_flat_workgroup_size: 512
    .name:           _Z8mega_fwd4Args
    .private_segment_fixed_size: 0
    .sgpr_count:     106
    .sgpr_spill_count: 235
    .symbol:         _Z8mega_fwd4Args.kd
    .uniform_work_group_size: 1
    .uses_dynamic_stack: false
    .vgpr_count:     256
    .vgpr_spill_count: 0
    .wavefront_size: 64
